# GEMM mainloop: 12 duplicate lgkmcnt(0) waits (compiler re-emitted right after the inline-asm wait) removed
# baseline (speedup 1.0000x reference)
; #define LDA(dst, b, h) _Pragma("unroll") for (int m = 0; m < 4; ++m) _Pragma("unroll") for (int k = 0; k < 2; ++k) \
;     dst[m][k] = *reinterpret_cast<const bf16x8*>((char*)SA(b, h) + lds_byte(wr * 64 + m * 16 + fr, k * 32 + fq * 8))
; #define LDB(dst, b, h) _Pragma("unroll") for (int n = 0; n < 2; ++n) _Pragma("unroll") for (int k = 0; k < 2; ++k) \
;     dst[n][k] = *reinterpret_cast<const bf16x8*>((char*)SB(b, h) + lds_byte(wc * 32 + n * 16 + fr, k * 32 + fq * 8))
; #define MMA(ai, bj, At_, Bt_) do { __builtin_amdgcn_s_setprio(1); \
;     _Pragma("unroll") for (int m = 0; m < 4; ++m) _Pragma("unroll") for (int n = 0; n < 2; ++n) _Pragma("unroll") for (int k = 0; k < 2; ++k) \
;       acc[ai][bj][m][n] = __builtin_amdgcn_mfma_f32_16x16x32_bf16(At_[m][k], Bt_[n][k], acc[ai][bj][m][n], 0, 0, 0); \
;     __builtin_amdgcn_s_setprio(0); } while (0)
; #define WAIT_V(n) asm volatile("s_waitcnt vmcnt(" #n ")" ::: "memory")
; #define WAIT_L(n) asm volatile("s_waitcnt lgkmcnt(" #n ")" ::: "memory")
; #define BAR __builtin_amdgcn_s_barrier()
; #define SCHED __builtin_amdgcn_sched_barrier(0)
; DI void gemm_tile(const GD& g, int pm, int pn, bf16_t* shm) {
;     ...
;   for (int t = 0; t < nt - 2; t += 2) {
;     LDB(B0, 0, 0); SCHED; LDA(At, 0, 0); STAGE(SA(1, 1), A, lda, brow + HALF, t + 1);
;     WAIT_L(8); BAR; WAIT_L(0); MMA(0, 0, At, B0); BAR; SCHED;
;     LDB(B1, 0, 1); STAGE(SB(0, 0), Bt, ldb, bh0, t + 2);
;     BAR; WAIT_L(0); MMA(0, 1, At, B1); BAR;
;     LDA(At, 0, 1); STAGE(SA(0, 0), A, lda, brow, t + 2);
;     BAR; WAIT_L(0); MMA(1, 0, At, B0); BAR; SCHED;
;     STAGE(SB(0, 1), Bt, ldb, bh1, t + 2);
;     WAIT_V(6); BAR; MMA(1, 1, At, B1); BAR;
.LBB0_460:
	ds_read_b128 v[154:157], v147
	ds_read_b128 v[158:161], v147 offset:1024
	ds_read_b128 v[162:165], v147 offset:2048
	ds_read_b128 v[166:169], v147 offset:3072
	s_add_u32 s67, s41, 0xffffff00
	s_addc_u32 s97, s63, -1
	s_add_u32 s82, s67, s6
	s_addc_u32 s83, s97, s7
	s_add_i32 m0, s70, 0xc000
	v_lshl_add_u64 v[202:203], s[82:83], 0, v[0:1]
	s_add_u32 s82, s67, s8
	v_add_u32_e32 v237, v146, v142
	s_addc_u32 s83, s97, s9
	ds_read_b128 v[170:173], v237
	ds_read_b128 v[174:177], v237 offset:1024
	ds_read_b128 v[178:181], v148
	ds_read_b128 v[182:185], v148 offset:1024
	ds_read_b128 v[186:189], v149
	ds_read_b128 v[190:193], v149 offset:1024
	ds_read_b128 v[194:197], v150
	ds_read_b128 v[198:201], v150 offset:1024
	global_load_lds_dwordx4 v[202:203], off
	v_lshl_add_u64 v[202:203], s[82:83], 0, v[0:1]
	s_add_i32 m0, s70, 0xe000
	s_nop 0
	global_load_lds_dwordx4 v[202:203], off
	s_waitcnt lgkmcnt(8)
	s_barrier
	s_waitcnt lgkmcnt(0)
	s_setprio 1
	v_mfma_f32_16x16x32_bf16 v[114:117], v[170:173], v[154:157], v[114:117]
	v_mfma_f32_16x16x32_bf16 v[126:129], v[170:173], v[162:165], v[126:129]
	v_mfma_f32_16x16x32_bf16 v[122:125], v[178:181], v[154:157], v[122:125]
	v_mfma_f32_16x16x32_bf16 v[118:121], v[178:181], v[162:165], v[118:121]
	v_mfma_f32_16x16x32_bf16 v[110:113], v[186:189], v[154:157], v[110:113]
	v_mfma_f32_16x16x32_bf16 v[106:109], v[186:189], v[162:165], v[106:109]
	v_mfma_f32_16x16x32_bf16 v[102:105], v[194:197], v[154:157], v[102:105]
	v_mfma_f32_16x16x32_bf16 v[98:101], v[194:197], v[162:165], v[98:101]
	v_mfma_f32_16x16x32_bf16 v[114:117], v[174:177], v[158:161], v[114:117]
	v_mfma_f32_16x16x32_bf16 v[126:129], v[174:177], v[166:169], v[126:129]
	v_mfma_f32_16x16x32_bf16 v[122:125], v[182:185], v[158:161], v[122:125]
	v_mfma_f32_16x16x32_bf16 v[118:121], v[182:185], v[166:169], v[118:121]
	v_mfma_f32_16x16x32_bf16 v[110:113], v[190:193], v[158:161], v[110:113]
	v_mfma_f32_16x16x32_bf16 v[106:109], v[190:193], v[166:169], v[106:109]
	v_mfma_f32_16x16x32_bf16 v[102:105], v[198:201], v[158:161], v[102:105]
	v_mfma_f32_16x16x32_bf16 v[98:101], v[198:201], v[166:169], v[98:101]
	s_setprio 0
	s_barrier
	s_add_i32 s3, s3, 2
	s_add_u32 s67, s58, 0xffffff80
	s_addc_u32 s97, s59, -1
	s_add_u32 s82, s67, s10
	s_addc_u32 s83, s97, s11
	v_lshl_add_u64 v[202:203], s[82:83], 0, v[0:1]
	s_add_u32 s82, s67, s12
	s_mov_b32 m0, s36
	s_addc_u32 s83, s97, s13
	ds_read_b128 v[238:241], v151
	ds_read_b128 v[242:245], v151 offset:1024
	ds_read_b128 v[246:249], v151 offset:2048
	ds_read_b128 v[214:217], v151 offset:3072
	global_load_lds_dwordx4 v[202:203], off
	v_lshl_add_u64 v[202:203], s[82:83], 0, v[0:1]
	s_mov_b32 m0, s66
	s_nop 0
	global_load_lds_dwordx4 v[202:203], off
	s_barrier
	s_waitcnt lgkmcnt(0)
	s_setprio 1
	v_mfma_f32_16x16x32_bf16 v[94:97], v[170:173], v[238:241], v[94:97]
	v_mfma_f32_16x16x32_bf16 v[90:93], v[170:173], v[246:249], v[90:93]
	v_mfma_f32_16x16x32_bf16 v[86:89], v[178:181], v[238:241], v[86:89]
	v_mfma_f32_16x16x32_bf16 v[82:85], v[178:181], v[246:249], v[82:85]
	v_mfma_f32_16x16x32_bf16 v[78:81], v[186:189], v[238:241], v[78:81]
	v_mfma_f32_16x16x32_bf16 v[74:77], v[186:189], v[246:249], v[74:77]
	v_mfma_f32_16x16x32_bf16 v[70:73], v[194:197], v[238:241], v[70:73]
	v_mfma_f32_16x16x32_bf16 v[66:69], v[194:197], v[246:249], v[66:69]
	v_mfma_f32_16x16x32_bf16 v[94:97], v[174:177], v[242:245], v[94:97]
	v_mfma_f32_16x16x32_bf16 v[90:93], v[174:177], v[214:217], v[90:93]
	v_mfma_f32_16x16x32_bf16 v[86:89], v[182:185], v[242:245], v[86:89]
	v_mfma_f32_16x16x32_bf16 v[82:85], v[182:185], v[214:217], v[82:85]
	v_mfma_f32_16x16x32_bf16 v[78:81], v[190:193], v[242:245], v[78:81]
	v_mfma_f32_16x16x32_bf16 v[74:77], v[190:193], v[214:217], v[74:77]
	v_mfma_f32_16x16x32_bf16 v[70:73], v[198:201], v[242:245], v[70:73]
	v_mfma_f32_16x16x32_bf16 v[66:69], v[198:201], v[214:217], v[66:69]
	s_setprio 0
	s_add_u32 vcc_lo, s41, 0xffffff80
	s_addc_u32 vcc_hi, s63, -1
	s_add_u32 s82, vcc_lo, s50
	s_addc_u32 s83, vcc_hi, s51
	v_lshl_add_u64 v[202:203], s[82:83], 0, v[0:1]
	s_add_u32 s82, vcc_lo, s52
	s_mov_b32 m0, s70
	s_addc_u32 s83, vcc_hi, s53
	s_barrier
	ds_read_b128 v[170:173], v237 offset:16384
	ds_read_b128 v[174:177], v237 offset:17408
	ds_read_b128 v[178:181], v148 offset:16384
	ds_read_b128 v[182:185], v148 offset:17408
	ds_read_b128 v[186:189], v149 offset:16384
	ds_read_b128 v[190:193], v149 offset:17408
	ds_read_b128 v[194:197], v150 offset:16384
	ds_read_b128 v[198:201], v150 offset:17408
	global_load_lds_dwordx4 v[202:203], off
	v_lshl_add_u64 v[202:203], s[82:83], 0, v[0:1]
	s_mov_b32 m0, s44
	s_nop 0
	global_load_lds_dwordx4 v[202:203], off
	s_barrier
	s_waitcnt lgkmcnt(0)
	s_setprio 1
	v_mfma_f32_16x16x32_bf16 v[62:65], v[170:173], v[154:157], v[62:65]
	v_mfma_f32_16x16x32_bf16 v[58:61], v[170:173], v[162:165], v[58:61]
	v_mfma_f32_16x16x32_bf16 v[54:57], v[178:181], v[154:157], v[54:57]
	v_mfma_f32_16x16x32_bf16 v[50:53], v[178:181], v[162:165], v[50:53]
	v_mfma_f32_16x16x32_bf16 v[46:49], v[186:189], v[154:157], v[46:49]
	v_mfma_f32_16x16x32_bf16 v[42:45], v[186:189], v[162:165], v[42:45]
	v_mfma_f32_16x16x32_bf16 v[38:41], v[194:197], v[154:157], v[38:41]
	v_mfma_f32_16x16x32_bf16 v[34:37], v[194:197], v[162:165], v[34:37]
	v_mfma_f32_16x16x32_bf16 v[62:65], v[174:177], v[158:161], v[62:65]
	v_mfma_f32_16x16x32_bf16 v[58:61], v[174:177], v[166:169], v[58:61]
	v_mfma_f32_16x16x32_bf16 v[54:57], v[182:185], v[158:161], v[54:57]
	v_mfma_f32_16x16x32_bf16 v[50:53], v[182:185], v[166:169], v[50:53]
	v_mfma_f32_16x16x32_bf16 v[46:49], v[190:193], v[158:161], v[46:49]
	v_mfma_f32_16x16x32_bf16 v[42:45], v[190:193], v[166:169], v[42:45]
	v_mfma_f32_16x16x32_bf16 v[38:41], v[198:201], v[158:161], v[38:41]
	v_mfma_f32_16x16x32_bf16 v[34:37], v[198:201], v[166:169], v[34:37]
	s_setprio 0
	s_barrier
; #define LDA(dst, b, h) _Pragma("unroll") for (int m = 0; m < 4; ++m) _Pragma("unroll") for (int k = 0; k < 2; ++k) \
;     dst[m][k] = *reinterpret_cast<const bf16x8*>((char*)SA(b, h) + lds_byte(wr * 64 + m * 16 + fr, k * 32 + fq * 8))
; #define LDB(dst, b, h) _Pragma("unroll") for (int n = 0; n < 2; ++n) _Pragma("unroll") for (int k = 0; k < 2; ++k) \
;     dst[n][k] = *reinterpret_cast<const bf16x8*>((char*)SB(b, h) + lds_byte(wc * 32 + n * 16 + fr, k * 32 + fq * 8))
; #define MMA(ai, bj, At_, Bt_) do { __builtin_amdgcn_s_setprio(1); \
;     _Pragma("unroll") for (int m = 0; m < 4; ++m) _Pragma("unroll") for (int n = 0; n < 2; ++n) _Pragma("unroll") for (int k = 0; k < 2; ++k) \
;       acc[ai][bj][m][n] = __builtin_amdgcn_mfma_f32_16x16x32_bf16(At_[m][k], Bt_[n][k], acc[ai][bj][m][n], 0, 0, 0); \
;     __builtin_amdgcn_s_setprio(0); } while (0)
; #define WAIT_V(n) asm volatile("s_waitcnt vmcnt(" #n ")" ::: "memory")
; #define WAIT_L(n) asm volatile("s_waitcnt lgkmcnt(" #n ")" ::: "memory")
; #define BAR __builtin_amdgcn_s_barrier()
; #define SCHED __builtin_amdgcn_sched_barrier(0)
; DI void gemm_tile(const GD& g, int pm, int pn, bf16_t* shm) {
;     ...
;     STAGE(SB(0, 1), Bt, ldb, bh1, t + 2);
;     WAIT_V(6); BAR; MMA(1, 1, At, B1); BAR;
;     LDB(B0, 1, 0); SCHED; LDA(At, 1, 0); STAGE(SA(0, 1), A, lda, brow + HALF, t + 2);
;     WAIT_L(8); BAR; WAIT_L(0); MMA(0, 0, At, B0); BAR; SCHED;
;     LDB(B1, 1, 1); STAGE(SB(1, 0), Bt, ldb, bh0, t + 3);
;     BAR; WAIT_L(0); MMA(0, 1, At, B1); BAR;
;     LDA(At, 1, 1); STAGE(SA(1, 0), A, lda, brow, t + 3);
;     BAR; WAIT_L(0); MMA(1, 0, At, B0); BAR; SCHED;
	s_add_u32 s82, s67, s54
	s_addc_u32 s83, s97, s55
	v_lshl_add_u64 v[154:155], s[82:83], 0, v[0:1]
	s_add_u32 s82, s67, s56
	s_mov_b32 m0, s69
	s_addc_u32 s83, s97, s57
	global_load_lds_dwordx4 v[154:155], off
	v_lshl_add_u64 v[154:155], s[82:83], 0, v[0:1]
	s_mov_b32 m0, s77
	s_nop 0
	global_load_lds_dwordx4 v[154:155], off
	s_waitcnt vmcnt(6)
	s_barrier
	s_setprio 1
	v_mfma_f32_16x16x32_bf16 v[30:33], v[170:173], v[238:241], v[30:33]
	v_mfma_f32_16x16x32_bf16 v[26:29], v[170:173], v[246:249], v[26:29]
	v_mfma_f32_16x16x32_bf16 v[22:25], v[178:181], v[238:241], v[22:25]
	v_mfma_f32_16x16x32_bf16 v[18:21], v[178:181], v[246:249], v[18:21]
	v_mfma_f32_16x16x32_bf16 v[14:17], v[186:189], v[238:241], v[14:17]
	v_mfma_f32_16x16x32_bf16 v[10:13], v[186:189], v[246:249], v[10:13]
	v_mfma_f32_16x16x32_bf16 v[6:9], v[194:197], v[238:241], v[6:9]
	v_mfma_f32_16x16x32_bf16 v[2:5], v[194:197], v[246:249], v[2:5]
	v_mfma_f32_16x16x32_bf16 v[30:33], v[174:177], v[242:245], v[30:33]
	v_mfma_f32_16x16x32_bf16 v[26:29], v[174:177], v[214:217], v[26:29]
	v_mfma_f32_16x16x32_bf16 v[22:25], v[182:185], v[242:245], v[22:25]
	v_mfma_f32_16x16x32_bf16 v[18:21], v[182:185], v[214:217], v[18:21]
	v_mfma_f32_16x16x32_bf16 v[14:17], v[190:193], v[242:245], v[14:17]
	v_mfma_f32_16x16x32_bf16 v[10:13], v[190:193], v[214:217], v[10:13]
	v_mfma_f32_16x16x32_bf16 v[6:9], v[198:201], v[242:245], v[6:9]
	v_mfma_f32_16x16x32_bf16 v[2:5], v[198:201], v[214:217], v[2:5]
	s_setprio 0
	s_barrier
	ds_read_b128 v[154:157], v152
	ds_read_b128 v[158:161], v152 offset:1024
	ds_read_b128 v[162:165], v152 offset:2048
	ds_read_b128 v[166:169], v152 offset:3072
	s_add_u32 s82, vcc_lo, s6
	s_addc_u32 s83, vcc_hi, s7
	v_lshl_add_u64 v[202:203], s[82:83], 0, v[0:1]
	s_add_u32 s82, vcc_lo, s8
	s_mov_b32 m0, s71
	s_addc_u32 s83, vcc_hi, s9
	ds_read_b128 v[170:173], v237 offset:32768
	ds_read_b128 v[174:177], v237 offset:33792
	ds_read_b128 v[178:181], v148 offset:32768
	ds_read_b128 v[182:185], v148 offset:33792
	ds_read_b128 v[186:189], v149 offset:32768
	ds_read_b128 v[190:193], v149 offset:33792
	ds_read_b128 v[194:197], v150 offset:32768
	ds_read_b128 v[198:201], v150 offset:33792
	global_load_lds_dwordx4 v[202:203], off
	v_lshl_add_u64 v[202:203], s[82:83], 0, v[0:1]
	s_mov_b32 m0, s65
	s_nop 0
	global_load_lds_dwordx4 v[202:203], off
	s_waitcnt lgkmcnt(8)
	s_barrier
	s_waitcnt lgkmcnt(0)
	s_setprio 1
	v_mfma_f32_16x16x32_bf16 v[114:117], v[170:173], v[154:157], v[114:117]
	v_mfma_f32_16x16x32_bf16 v[126:129], v[170:173], v[162:165], v[126:129]
	v_mfma_f32_16x16x32_bf16 v[122:125], v[178:181], v[154:157], v[122:125]
	v_mfma_f32_16x16x32_bf16 v[118:121], v[178:181], v[162:165], v[118:121]
	v_mfma_f32_16x16x32_bf16 v[110:113], v[186:189], v[154:157], v[110:113]
	v_mfma_f32_16x16x32_bf16 v[106:109], v[186:189], v[162:165], v[106:109]
	v_mfma_f32_16x16x32_bf16 v[102:105], v[194:197], v[154:157], v[102:105]
	v_mfma_f32_16x16x32_bf16 v[98:101], v[194:197], v[162:165], v[98:101]
	v_mfma_f32_16x16x32_bf16 v[114:117], v[174:177], v[158:161], v[114:117]
	v_mfma_f32_16x16x32_bf16 v[126:129], v[174:177], v[166:169], v[126:129]
	v_mfma_f32_16x16x32_bf16 v[122:125], v[182:185], v[158:161], v[122:125]
	v_mfma_f32_16x16x32_bf16 v[118:121], v[182:185], v[166:169], v[118:121]
	v_mfma_f32_16x16x32_bf16 v[110:113], v[190:193], v[158:161], v[110:113]
	v_mfma_f32_16x16x32_bf16 v[106:109], v[190:193], v[166:169], v[106:109]
	v_mfma_f32_16x16x32_bf16 v[102:105], v[198:201], v[158:161], v[102:105]
	v_mfma_f32_16x16x32_bf16 v[98:101], v[198:201], v[166:169], v[98:101]
	s_setprio 0
	s_barrier
	s_add_u32 s82, s58, s10
	s_addc_u32 s83, s59, s11
	v_lshl_add_u64 v[202:203], s[82:83], 0, v[0:1]
	s_add_u32 s82, s58, s12
	s_mov_b32 m0, s96
	s_addc_u32 s83, s59, s13
	ds_read_b128 v[214:217], v153
	ds_read_b128 v[238:241], v153 offset:1024
	ds_read_b128 v[242:245], v153 offset:2048
	ds_read_b128 v[246:249], v153 offset:3072
	global_load_lds_dwordx4 v[202:203], off
	v_lshl_add_u64 v[202:203], s[82:83], 0, v[0:1]
	s_mov_b32 m0, s60
	s_nop 0
	global_load_lds_dwordx4 v[202:203], off
	s_barrier
	s_waitcnt lgkmcnt(0)
	s_setprio 1
	v_mfma_f32_16x16x32_bf16 v[94:97], v[170:173], v[214:217], v[94:97]
	v_mfma_f32_16x16x32_bf16 v[90:93], v[170:173], v[242:245], v[90:93]
	v_mfma_f32_16x16x32_bf16 v[86:89], v[178:181], v[214:217], v[86:89]
	v_mfma_f32_16x16x32_bf16 v[82:85], v[178:181], v[242:245], v[82:85]
	v_mfma_f32_16x16x32_bf16 v[78:81], v[186:189], v[214:217], v[78:81]
	v_mfma_f32_16x16x32_bf16 v[74:77], v[186:189], v[242:245], v[74:77]
	v_mfma_f32_16x16x32_bf16 v[70:73], v[194:197], v[214:217], v[70:73]
	v_mfma_f32_16x16x32_bf16 v[66:69], v[194:197], v[242:245], v[66:69]
	v_mfma_f32_16x16x32_bf16 v[94:97], v[174:177], v[238:241], v[94:97]
	v_mfma_f32_16x16x32_bf16 v[90:93], v[174:177], v[246:249], v[90:93]
	v_mfma_f32_16x16x32_bf16 v[86:89], v[182:185], v[238:241], v[86:89]
	v_mfma_f32_16x16x32_bf16 v[82:85], v[182:185], v[246:249], v[82:85]
	v_mfma_f32_16x16x32_bf16 v[78:81], v[190:193], v[238:241], v[78:81]
	v_mfma_f32_16x16x32_bf16 v[74:77], v[190:193], v[246:249], v[74:77]
	v_mfma_f32_16x16x32_bf16 v[70:73], v[198:201], v[238:241], v[70:73]
	v_mfma_f32_16x16x32_bf16 v[66:69], v[198:201], v[246:249], v[66:69]
	s_setprio 0
	s_add_u32 s82, s41, s50
	s_addc_u32 s83, s63, s51
	v_lshl_add_u64 v[202:203], s[82:83], 0, v[0:1]
	s_add_u32 s82, s41, s52
	s_mov_b32 m0, s25
	s_addc_u32 s83, s63, s53
	s_barrier
; #define LDA(dst, b, h) _Pragma("unroll") for (int m = 0; m < 4; ++m) _Pragma("unroll") for (int k = 0; k < 2; ++k) \
;     dst[m][k] = *reinterpret_cast<const bf16x8*>((char*)SA(b, h) + lds_byte(wr * 64 + m * 16 + fr, k * 32 + fq * 8))
; #define LDB(dst, b, h) _Pragma("unroll") for (int n = 0; n < 2; ++n) _Pragma("unroll") for (int k = 0; k < 2; ++k) \
;     dst[n][k] = *reinterpret_cast<const bf16x8*>((char*)SB(b, h) + lds_byte(wc * 32 + n * 16 + fr, k * 32 + fq * 8))
; #define MMA(ai, bj, At_, Bt_) do { __builtin_amdgcn_s_setprio(1); \
;     _Pragma("unroll") for (int m = 0; m < 4; ++m) _Pragma("unroll") for (int n = 0; n < 2; ++n) _Pragma("unroll") for (int k = 0; k < 2; ++k) \
;       acc[ai][bj][m][n] = __builtin_amdgcn_mfma_f32_16x16x32_bf16(At_[m][k], Bt_[n][k], acc[ai][bj][m][n], 0, 0, 0); \
;     __builtin_amdgcn_s_setprio(0); } while (0)
; #define WAIT_V(n) asm volatile("s_waitcnt vmcnt(" #n ")" ::: "memory")
; #define WAIT_L(n) asm volatile("s_waitcnt lgkmcnt(" #n ")" ::: "memory")
; #define BAR __builtin_amdgcn_s_barrier()
; #define SCHED __builtin_amdgcn_sched_barrier(0)
; DI void gemm_tile(const GD& g, int pm, int pn, bf16_t* shm) {
;     ...
;     LDA(At, 1, 1); STAGE(SA(1, 0), A, lda, brow, t + 3);
;     BAR; WAIT_L(0); MMA(1, 0, At, B0); BAR; SCHED;
;     STAGE(SB(1, 1), Bt, ldb, bh1, t + 3);
;     WAIT_V(6); BAR; MMA(1, 1, At, B1); BAR;
;   }
;   { LDB(B0, 0, 0); LDA(At, 0, 0); STAGE(SA(1, 1), A, lda, brow + HALF, nt - 1);
;     BAR; WAIT_L(0); MMA(0, 0, At, B0); BAR;
	ds_read_b128 v[170:173], v237 offset:49152
	ds_read_b128 v[174:177], v237 offset:50176
	ds_read_b128 v[178:181], v148 offset:49152
	ds_read_b128 v[182:185], v148 offset:50176
	ds_read_b128 v[186:189], v149 offset:49152
	ds_read_b128 v[190:193], v149 offset:50176
	ds_read_b128 v[194:197], v150 offset:49152
	ds_read_b128 v[198:201], v150 offset:50176
	global_load_lds_dwordx4 v[202:203], off
	v_lshl_add_u64 v[202:203], s[82:83], 0, v[0:1]
	s_mov_b32 m0, s61
	s_nop 0
	global_load_lds_dwordx4 v[202:203], off
	s_barrier
	s_waitcnt lgkmcnt(0)
	s_setprio 1
	v_mfma_f32_16x16x32_bf16 v[62:65], v[170:173], v[154:157], v[62:65]
	v_mfma_f32_16x16x32_bf16 v[58:61], v[170:173], v[162:165], v[58:61]
	v_mfma_f32_16x16x32_bf16 v[54:57], v[178:181], v[154:157], v[54:57]
	v_mfma_f32_16x16x32_bf16 v[50:53], v[178:181], v[162:165], v[50:53]
	v_mfma_f32_16x16x32_bf16 v[46:49], v[186:189], v[154:157], v[46:49]
	v_mfma_f32_16x16x32_bf16 v[42:45], v[186:189], v[162:165], v[42:45]
	v_mfma_f32_16x16x32_bf16 v[38:41], v[194:197], v[154:157], v[38:41]
	v_mfma_f32_16x16x32_bf16 v[34:37], v[194:197], v[162:165], v[34:37]
	v_mfma_f32_16x16x32_bf16 v[62:65], v[174:177], v[158:161], v[62:65]
	v_mfma_f32_16x16x32_bf16 v[58:61], v[174:177], v[166:169], v[58:61]
	v_mfma_f32_16x16x32_bf16 v[54:57], v[182:185], v[158:161], v[54:57]
	v_mfma_f32_16x16x32_bf16 v[50:53], v[182:185], v[166:169], v[50:53]
	v_mfma_f32_16x16x32_bf16 v[46:49], v[190:193], v[158:161], v[46:49]
	v_mfma_f32_16x16x32_bf16 v[42:45], v[190:193], v[166:169], v[42:45]
	v_mfma_f32_16x16x32_bf16 v[38:41], v[198:201], v[158:161], v[38:41]
	v_mfma_f32_16x16x32_bf16 v[34:37], v[198:201], v[166:169], v[34:37]
	s_setprio 0
	s_barrier
	s_add_u32 s82, s58, s54
	s_addc_u32 s83, s59, s55
	v_lshl_add_u64 v[154:155], s[82:83], 0, v[0:1]
	s_add_u32 s82, s58, s56
	s_mov_b32 m0, s62
	s_addc_u32 s83, s59, s57
	global_load_lds_dwordx4 v[154:155], off
	v_lshl_add_u64 v[154:155], s[82:83], 0, v[0:1]
	s_mov_b32 m0, s40
	s_nop 0
	global_load_lds_dwordx4 v[154:155], off
	s_waitcnt vmcnt(6)
	s_barrier
	s_setprio 1
	v_mfma_f32_16x16x32_bf16 v[30:33], v[170:173], v[214:217], v[30:33]
	v_mfma_f32_16x16x32_bf16 v[26:29], v[170:173], v[242:245], v[26:29]
	v_mfma_f32_16x16x32_bf16 v[22:25], v[178:181], v[214:217], v[22:25]
	v_mfma_f32_16x16x32_bf16 v[18:21], v[178:181], v[242:245], v[18:21]
	v_mfma_f32_16x16x32_bf16 v[14:17], v[186:189], v[214:217], v[14:17]
	v_mfma_f32_16x16x32_bf16 v[10:13], v[186:189], v[242:245], v[10:13]
	v_mfma_f32_16x16x32_bf16 v[6:9], v[194:197], v[214:217], v[6:9]
	v_mfma_f32_16x16x32_bf16 v[2:5], v[194:197], v[242:245], v[2:5]
	v_mfma_f32_16x16x32_bf16 v[30:33], v[174:177], v[238:241], v[30:33]
	v_mfma_f32_16x16x32_bf16 v[26:29], v[174:177], v[246:249], v[26:29]
	v_mfma_f32_16x16x32_bf16 v[22:25], v[182:185], v[238:241], v[22:25]
	v_mfma_f32_16x16x32_bf16 v[18:21], v[182:185], v[246:249], v[18:21]
	v_mfma_f32_16x16x32_bf16 v[14:17], v[190:193], v[238:241], v[14:17]
	v_mfma_f32_16x16x32_bf16 v[10:13], v[190:193], v[246:249], v[10:13]
	v_mfma_f32_16x16x32_bf16 v[6:9], v[198:201], v[238:241], v[6:9]
	v_mfma_f32_16x16x32_bf16 v[2:5], v[198:201], v[246:249], v[2:5]
	s_setprio 0
	s_add_u32 s58, s58, 0x100
	s_addc_u32 s59, s59, 0
	s_add_u32 s41, s41, 0x100
	s_addc_u32 s63, s63, 0
	s_cmp_lt_u32 s3, s2
	s_barrier
	s_cbranch_scc1 .LBB0_460
	v_mov_b32_e32 v146, v143
	v_mov_b32_e32 v147, v144
	v_mov_b32_e32 v148, v145
	v_mov_b32_e32 v149, v142
.LBB0_462:
	v_readlane_b32 s56, v253, 39
	v_readlane_b32 s57, v253, 40
	s_add_i32 s56, s24, -1
	s_lshl_b64 s[2:3], s[56:57], 7
	s_add_u32 s2, s0, s2
	v_add_u32_e32 v142, v141, v131
	v_add_u32_e32 v150, v141, v146
	v_add_u32_e32 v154, v141, v147
	v_add_u32_e32 v141, v141, v148
	s_addc_u32 s3, s1, s3
	ds_read_b128 v[142:145], v142
	ds_read_b128 v[150:153], v150
	ds_read_b128 v[154:157], v154
	ds_read_b128 v[158:161], v141
	v_add_u32_e32 v141, 0, v133
	s_add_u32 s0, s2, s6
	v_add_u32_e32 v203, v141, v134
	v_add_u32_e32 v134, 0, v133
	s_addc_u32 s1, s3, s7
	s_add_i32 m0, s70, 0xc000
	v_add_u32_e32 v214, v134, v135
	v_add_u32_e32 v215, v134, v136
	v_add_u32_e32 v134, 0, v133
	v_add_u32_e32 v133, 0, v133
	v_lshl_add_u64 v[186:187], s[0:1], 0, v[0:1]
	s_add_u32 s0, s2, s8
	v_add_u32_e32 v202, v141, v149
	v_add_u32_e32 v216, v134, v137
	v_add_u32_e32 v237, v133, v139
	s_addc_u32 s1, s3, s9
	ds_read_b128 v[162:165], v202
	ds_read_b128 v[166:169], v203
	ds_read_b128 v[170:173], v214
	ds_read_b128 v[174:177], v215
	v_add_u32_e32 v217, v134, v138
	ds_read_b128 v[134:137], v216
	ds_read_b128 v[178:181], v217
	v_add_u32_e32 v133, v133, v140
	ds_read_b128 v[138:141], v237
	ds_read_b128 v[182:185], v133
	global_load_lds_dwordx4 v[186:187], off
	v_lshl_add_u64 v[186:187], s[0:1], 0, v[0:1]
	s_add_i32 m0, s70, 0xe000
	s_nop 0
	global_load_lds_dwordx4 v[186:187], off
	s_barrier
	s_waitcnt lgkmcnt(0)
	s_setprio 1
	v_mfma_f32_16x16x32_bf16 v[114:117], v[162:165], v[142:145], v[114:117]
	v_mfma_f32_16x16x32_bf16 v[110:113], v[134:137], v[142:145], v[110:113]
	v_mfma_f32_16x16x32_bf16 v[106:109], v[134:137], v[154:157], v[106:109]
	v_mfma_f32_16x16x32_bf16 v[102:105], v[138:141], v[142:145], v[102:105]
	v_mfma_f32_16x16x32_bf16 v[98:101], v[138:141], v[154:157], v[98:101]
	v_mfma_f32_16x16x32_bf16 v[114:117], v[166:169], v[150:153], v[114:117]
	v_mfma_f32_16x16x32_bf16 v[126:129], v[162:165], v[154:157], v[126:129]
	v_mfma_f32_16x16x32_bf16 v[122:125], v[170:173], v[142:145], v[122:125]
	v_mfma_f32_16x16x32_bf16 v[118:121], v[170:173], v[154:157], v[118:121]
	v_mfma_f32_16x16x32_bf16 v[110:113], v[178:181], v[150:153], v[110:113]
	v_mfma_f32_16x16x32_bf16 v[106:109], v[178:181], v[158:161], v[106:109]
	v_mfma_f32_16x16x32_bf16 v[102:105], v[182:185], v[150:153], v[102:105]
	v_mfma_f32_16x16x32_bf16 v[98:101], v[182:185], v[158:161], v[98:101]
	v_mfma_f32_16x16x32_bf16 v[186:189], v[166:169], v[158:161], v[126:129]
	v_mfma_f32_16x16x32_bf16 v[190:193], v[174:177], v[150:153], v[122:125]
	v_mfma_f32_16x16x32_bf16 v[194:197], v[174:177], v[158:161], v[118:121]
	s_setprio 0
	s_add_i32 s0, 0, 0x14000
	v_add_u32_e32 v0, s0, v132
	v_add_u32_e32 v118, v0, v131
	v_add_u32_e32 v122, v0, v146
	v_add_u32_e32 v126, v0, v147
	s_barrier
; #define LDA(dst, b, h) _Pragma("unroll") for (int m = 0; m < 4; ++m) _Pragma("unroll") for (int k = 0; k < 2; ++k) \
;     dst[m][k] = *reinterpret_cast<const bf16x8*>((char*)SA(b, h) + lds_byte(wr * 64 + m * 16 + fr, k * 32 + fq * 8))
; #define LDB(dst, b, h) _Pragma("unroll") for (int n = 0; n < 2; ++n) _Pragma("unroll") for (int k = 0; k < 2; ++k) \
;     dst[n][k] = *reinterpret_cast<const bf16x8*>((char*)SB(b, h) + lds_byte(wc * 32 + n * 16 + fr, k * 32 + fq * 8))
; #define MMA(ai, bj, At_, Bt_) do { __builtin_amdgcn_s_setprio(1); \
;     _Pragma("unroll") for (int m = 0; m < 4; ++m) _Pragma("unroll") for (int n = 0; n < 2; ++n) _Pragma("unroll") for (int k = 0; k < 2; ++k) \
;       acc[ai][bj][m][n] = __builtin_amdgcn_mfma_f32_16x16x32_bf16(At_[m][k], Bt_[n][k], acc[ai][bj][m][n], 0, 0, 0); \
;     __builtin_amdgcn_s_setprio(0); } while (0)
; #define WAIT_V(n) asm volatile("s_waitcnt vmcnt(" #n ")" ::: "memory")
; #define WAIT_L(n) asm volatile("s_waitcnt lgkmcnt(" #n ")" ::: "memory")
; #define BAR __builtin_amdgcn_s_barrier()
; DI void gemm_tile(const GD& g, int pm, int pn, bf16_t* shm) {
;     ...
;     LDB(B1, 0, 1); BAR; WAIT_L(0); MMA(0, 1, At, B1); BAR;
;     LDA(At, 0, 1); WAIT_V(4); BAR; WAIT_L(0); MMA(1, 0, At, B0); MMA(1, 1, At, B1); BAR; }
;   { LDB(B0, 1, 0); LDA(At, 1, 0); WAIT_V(2); BAR; WAIT_L(0); MMA(0, 0, At, B0); BAR;
	ds_read_b128 v[118:121], v118
	ds_read_b128 v[122:125], v122
	v_add_u32_e32 v0, v0, v148
	ds_read_b128 v[126:129], v126
	ds_read_b128 v[198:201], v0
	s_barrier
	s_waitcnt lgkmcnt(0)
	s_setprio 1
	v_mfma_f32_16x16x32_bf16 v[94:97], v[162:165], v[118:121], v[94:97]
	v_mfma_f32_16x16x32_bf16 v[90:93], v[162:165], v[126:129], v[90:93]
	v_mfma_f32_16x16x32_bf16 v[86:89], v[170:173], v[118:121], v[86:89]
	v_mfma_f32_16x16x32_bf16 v[82:85], v[170:173], v[126:129], v[82:85]
	v_mfma_f32_16x16x32_bf16 v[78:81], v[134:137], v[118:121], v[78:81]
	v_mfma_f32_16x16x32_bf16 v[74:77], v[134:137], v[126:129], v[74:77]
	v_mfma_f32_16x16x32_bf16 v[70:73], v[138:141], v[118:121], v[70:73]
	v_mfma_f32_16x16x32_bf16 v[66:69], v[138:141], v[126:129], v[66:69]
	v_mfma_f32_16x16x32_bf16 v[94:97], v[166:169], v[122:125], v[94:97]
	v_mfma_f32_16x16x32_bf16 v[90:93], v[166:169], v[198:201], v[90:93]
	v_mfma_f32_16x16x32_bf16 v[86:89], v[174:177], v[122:125], v[86:89]
	v_mfma_f32_16x16x32_bf16 v[82:85], v[174:177], v[198:201], v[82:85]
	v_mfma_f32_16x16x32_bf16 v[78:81], v[178:181], v[122:125], v[78:81]
	v_mfma_f32_16x16x32_bf16 v[74:77], v[178:181], v[198:201], v[74:77]
	v_mfma_f32_16x16x32_bf16 v[70:73], v[182:185], v[122:125], v[70:73]
	v_mfma_f32_16x16x32_bf16 v[66:69], v[182:185], v[198:201], v[66:69]
	s_setprio 0
	s_barrier
	ds_read_b128 v[134:137], v202 offset:16384
	ds_read_b128 v[138:141], v203 offset:16384
	ds_read_b128 v[162:165], v214 offset:16384
	ds_read_b128 v[166:169], v215 offset:16384
	ds_read_b128 v[170:173], v216 offset:16384
	ds_read_b128 v[174:177], v217 offset:16384
	ds_read_b128 v[178:181], v237 offset:16384
	ds_read_b128 v[182:185], v133 offset:16384
	s_waitcnt vmcnt(4)
	s_barrier
	s_waitcnt lgkmcnt(0)
	s_setprio 1
	v_mfma_f32_16x16x32_bf16 v[62:65], v[134:137], v[142:145], v[62:65]
	v_mfma_f32_16x16x32_bf16 v[58:61], v[134:137], v[154:157], v[58:61]
	v_mfma_f32_16x16x32_bf16 v[54:57], v[162:165], v[142:145], v[54:57]
	v_mfma_f32_16x16x32_bf16 v[50:53], v[162:165], v[154:157], v[50:53]
	v_mfma_f32_16x16x32_bf16 v[46:49], v[170:173], v[142:145], v[46:49]
	v_mfma_f32_16x16x32_bf16 v[42:45], v[170:173], v[154:157], v[42:45]
	v_mfma_f32_16x16x32_bf16 v[38:41], v[178:181], v[142:145], v[38:41]
	v_mfma_f32_16x16x32_bf16 v[34:37], v[178:181], v[154:157], v[34:37]
	v_mfma_f32_16x16x32_bf16 v[62:65], v[138:141], v[150:153], v[62:65]
	v_mfma_f32_16x16x32_bf16 v[58:61], v[138:141], v[158:161], v[58:61]
	v_mfma_f32_16x16x32_bf16 v[54:57], v[166:169], v[150:153], v[54:57]
	v_mfma_f32_16x16x32_bf16 v[50:53], v[166:169], v[158:161], v[50:53]
	v_mfma_f32_16x16x32_bf16 v[46:49], v[174:177], v[150:153], v[46:49]
	v_mfma_f32_16x16x32_bf16 v[42:45], v[174:177], v[158:161], v[42:45]
	v_mfma_f32_16x16x32_bf16 v[38:41], v[182:185], v[150:153], v[38:41]
	v_mfma_f32_16x16x32_bf16 v[34:37], v[182:185], v[158:161], v[34:37]
	s_setprio 0
	s_setprio 1
	v_mfma_f32_16x16x32_bf16 v[30:33], v[134:137], v[118:121], v[30:33]
	v_mfma_f32_16x16x32_bf16 v[26:29], v[134:137], v[126:129], v[26:29]
	v_mfma_f32_16x16x32_bf16 v[22:25], v[162:165], v[118:121], v[22:25]
	v_mfma_f32_16x16x32_bf16 v[18:21], v[162:165], v[126:129], v[18:21]
	v_mfma_f32_16x16x32_bf16 v[30:33], v[138:141], v[122:125], v[30:33]
	v_mfma_f32_16x16x32_bf16 v[26:29], v[138:141], v[198:201], v[26:29]
	v_mfma_f32_16x16x32_bf16 v[22:25], v[166:169], v[122:125], v[22:25]
	v_mfma_f32_16x16x32_bf16 v[18:21], v[166:169], v[198:201], v[18:21]
	v_mfma_f32_16x16x32_bf16 v[14:17], v[170:173], v[118:121], v[14:17]
	v_mfma_f32_16x16x32_bf16 v[10:13], v[170:173], v[126:129], v[10:13]
	v_mfma_f32_16x16x32_bf16 v[6:9], v[178:181], v[118:121], v[6:9]
	v_mfma_f32_16x16x32_bf16 v[2:5], v[178:181], v[126:129], v[2:5]
	v_mfma_f32_16x16x32_bf16 v[134:137], v[174:177], v[122:125], v[14:17]
	v_mfma_f32_16x16x32_bf16 v[138:141], v[174:177], v[198:201], v[10:13]
	v_mfma_f32_16x16x32_bf16 v[142:145], v[182:185], v[122:125], v[6:9]
	v_mfma_f32_16x16x32_bf16 v[150:153], v[182:185], v[198:201], v[2:5]
	s_setprio 0
	s_add_i32 s0, 0, 0x18000
	v_add_u32_e32 v0, s0, v132
	s_nop 0
	v_add_u32_e32 v2, v0, v131
	s_barrier
	v_add_u32_e32 v3, v0, v146
	ds_read_b128 v[154:157], v2
	ds_read_b128 v[158:161], v3
	v_add_u32_e32 v2, v0, v147
	v_add_u32_e32 v0, v0, v148
	ds_read_b128 v[162:165], v2
	ds_read_b128 v[166:169], v0
	ds_read_b128 v[2:5], v202 offset:32768
	ds_read_b128 v[6:9], v203 offset:32768
	ds_read_b128 v[10:13], v214 offset:32768
	ds_read_b128 v[14:17], v215 offset:32768
	ds_read_b128 v[170:173], v216 offset:32768
	ds_read_b128 v[174:177], v217 offset:32768
	ds_read_b128 v[178:181], v237 offset:32768
	ds_read_b128 v[182:185], v133 offset:32768
	s_waitcnt vmcnt(2)
	s_barrier
; #define LDA(dst, b, h) _Pragma("unroll") for (int m = 0; m < 4; ++m) _Pragma("unroll") for (int k = 0; k < 2; ++k) \
;     dst[m][k] = *reinterpret_cast<const bf16x8*>((char*)SA(b, h) + lds_byte(wr * 64 + m * 16 + fr, k * 32 + fq * 8))
; #define LDB(dst, b, h) _Pragma("unroll") for (int n = 0; n < 2; ++n) _Pragma("unroll") for (int k = 0; k < 2; ++k) \
;     dst[n][k] = *reinterpret_cast<const bf16x8*>((char*)SB(b, h) + lds_byte(wc * 32 + n * 16 + fr, k * 32 + fq * 8))
; #define MMA(ai, bj, At_, Bt_) do { __builtin_amdgcn_s_setprio(1); \
;     _Pragma("unroll") for (int m = 0; m < 4; ++m) _Pragma("unroll") for (int n = 0; n < 2; ++n) _Pragma("unroll") for (int k = 0; k < 2; ++k) \
;       acc[ai][bj][m][n] = __builtin_amdgcn_mfma_f32_16x16x32_bf16(At_[m][k], Bt_[n][k], acc[ai][bj][m][n], 0, 0, 0); \
;     __builtin_amdgcn_s_setprio(0); } while (0)
; #define WAIT_V(n) asm volatile("s_waitcnt vmcnt(" #n ")" ::: "memory")
; #define WAIT_L(n) asm volatile("s_waitcnt lgkmcnt(" #n ")" ::: "memory")
; #define BAR __builtin_amdgcn_s_barrier()
; DI void gemm_tile(const GD& g, int pm, int pn, bf16_t* shm) {
;     ...
;   { LDB(B0, 1, 0); LDA(At, 1, 0); WAIT_V(2); BAR; WAIT_L(0); MMA(0, 0, At, B0); BAR;
;     LDB(B1, 1, 1); WAIT_V(0); BAR; WAIT_L(0); MMA(0, 1, At, B1); BAR;
;     LDA(At, 1, 1); BAR; WAIT_L(0); MMA(1, 0, At, B0); MMA(1, 1, At, B1); BAR; }
;   if (wr == 0) BAR;
	s_waitcnt lgkmcnt(0)
	s_setprio 1
	v_mfma_f32_16x16x32_bf16 v[114:117], v[2:5], v[154:157], v[114:117]
	v_mfma_f32_16x16x32_bf16 v[126:129], v[6:9], v[158:161], v[114:117]
	v_mfma_f32_16x16x32_bf16 v[114:117], v[2:5], v[162:165], v[186:189]
	v_mfma_f32_16x16x32_bf16 v[122:125], v[6:9], v[166:169], v[114:117]
	v_mfma_f32_16x16x32_bf16 v[114:117], v[10:13], v[154:157], v[190:193]
	v_mfma_f32_16x16x32_bf16 v[118:121], v[14:17], v[158:161], v[114:117]
	v_mfma_f32_16x16x32_bf16 v[114:117], v[10:13], v[162:165], v[194:197]
	v_mfma_f32_16x16x32_bf16 v[110:113], v[170:173], v[154:157], v[110:113]
	v_mfma_f32_16x16x32_bf16 v[106:109], v[170:173], v[162:165], v[106:109]
	v_mfma_f32_16x16x32_bf16 v[102:105], v[178:181], v[154:157], v[102:105]
	v_mfma_f32_16x16x32_bf16 v[98:101], v[178:181], v[162:165], v[98:101]
	v_mfma_f32_16x16x32_bf16 v[114:117], v[14:17], v[166:169], v[114:117]
	v_mfma_f32_16x16x32_bf16 v[110:113], v[174:177], v[158:161], v[110:113]
	v_mfma_f32_16x16x32_bf16 v[106:109], v[174:177], v[166:169], v[106:109]
	v_mfma_f32_16x16x32_bf16 v[102:105], v[182:185], v[158:161], v[102:105]
	v_mfma_f32_16x16x32_bf16 v[98:101], v[182:185], v[166:169], v[98:101]
	s_setprio 0
	s_add_i32 s0, 0, 0x1c000
	v_add_u32_e32 v0, s0, v132
	v_add_u32_e32 v131, v0, v131
	s_barrier
	v_add_u32_e32 v132, v0, v146
	ds_read_b128 v[186:189], v131
	ds_read_b128 v[190:193], v132
	v_add_u32_e32 v131, v0, v147
	v_add_u32_e32 v0, v0, v148
	ds_read_b128 v[146:149], v131
	ds_read_b128 v[194:197], v0
	s_waitcnt vmcnt(0)
	s_barrier
	s_waitcnt lgkmcnt(0)
	s_setprio 1
	v_mfma_f32_16x16x32_bf16 v[94:97], v[2:5], v[186:189], v[94:97]
	v_mfma_f32_16x16x32_bf16 v[2:5], v[2:5], v[146:149], v[90:93]
	v_mfma_f32_16x16x32_bf16 v[90:93], v[6:9], v[194:197], v[2:5]
	v_mfma_f32_16x16x32_bf16 v[2:5], v[10:13], v[186:189], v[86:89]
	v_mfma_f32_16x16x32_bf16 v[86:89], v[14:17], v[190:193], v[2:5]
	v_mfma_f32_16x16x32_bf16 v[2:5], v[10:13], v[146:149], v[82:85]
	v_mfma_f32_16x16x32_bf16 v[82:85], v[14:17], v[194:197], v[2:5]
	v_mfma_f32_16x16x32_bf16 v[2:5], v[170:173], v[186:189], v[78:81]
	v_mfma_f32_16x16x32_bf16 v[14:17], v[174:177], v[190:193], v[2:5]
	v_mfma_f32_16x16x32_bf16 v[2:5], v[170:173], v[146:149], v[74:77]
	v_mfma_f32_16x16x32_bf16 v[10:13], v[174:177], v[194:197], v[2:5]
	v_mfma_f32_16x16x32_bf16 v[2:5], v[178:181], v[186:189], v[70:73]
	v_mfma_f32_16x16x32_bf16 v[94:97], v[6:9], v[190:193], v[94:97]
	v_mfma_f32_16x16x32_bf16 v[6:9], v[182:185], v[190:193], v[2:5]
	v_mfma_f32_16x16x32_bf16 v[2:5], v[178:181], v[146:149], v[66:69]
	v_mfma_f32_16x16x32_bf16 v[2:5], v[182:185], v[194:197], v[2:5]
	s_setprio 0
	s_barrier
	ds_read_b128 v[170:173], v202 offset:49152
	ds_read_b128 v[174:177], v203 offset:49152
	ds_read_b128 v[178:181], v214 offset:49152
	ds_read_b128 v[182:185], v215 offset:49152
	ds_read_b128 v[198:201], v216 offset:49152
	ds_read_b128 v[214:217], v217 offset:49152
	ds_read_b128 v[238:241], v237 offset:49152
	ds_read_b128 v[242:245], v133 offset:49152
	s_barrier
	s_waitcnt lgkmcnt(0)
	s_setprio 1
	v_mfma_f32_16x16x32_bf16 v[62:65], v[170:173], v[154:157], v[62:65]
	v_mfma_f32_16x16x32_bf16 v[58:61], v[170:173], v[162:165], v[58:61]
	v_mfma_f32_16x16x32_bf16 v[54:57], v[178:181], v[154:157], v[54:57]
	v_mfma_f32_16x16x32_bf16 v[50:53], v[178:181], v[162:165], v[50:53]
	v_mfma_f32_16x16x32_bf16 v[46:49], v[198:201], v[154:157], v[46:49]
	v_mfma_f32_16x16x32_bf16 v[42:45], v[198:201], v[162:165], v[42:45]
	v_mfma_f32_16x16x32_bf16 v[38:41], v[238:241], v[154:157], v[38:41]
	v_mfma_f32_16x16x32_bf16 v[34:37], v[238:241], v[162:165], v[34:37]
	v_mfma_f32_16x16x32_bf16 v[78:81], v[174:177], v[158:161], v[62:65]
	v_mfma_f32_16x16x32_bf16 v[74:77], v[174:177], v[166:169], v[58:61]
	v_mfma_f32_16x16x32_bf16 v[70:73], v[182:185], v[158:161], v[54:57]
	v_mfma_f32_16x16x32_bf16 v[66:69], v[182:185], v[166:169], v[50:53]
	v_mfma_f32_16x16x32_bf16 v[62:65], v[214:217], v[158:161], v[46:49]
	v_mfma_f32_16x16x32_bf16 v[58:61], v[214:217], v[166:169], v[42:45]
	v_mfma_f32_16x16x32_bf16 v[54:57], v[242:245], v[158:161], v[38:41]
	v_mfma_f32_16x16x32_bf16 v[50:53], v[242:245], v[166:169], v[34:37]
	s_setprio 0
	s_setprio 1
	v_mfma_f32_16x16x32_bf16 v[18:21], v[178:181], v[146:149], v[18:21]
	v_mfma_f32_16x16x32_bf16 v[30:33], v[170:173], v[186:189], v[30:33]
	v_mfma_f32_16x16x32_bf16 v[34:37], v[182:185], v[194:197], v[18:21]
	v_mfma_f32_16x16x32_bf16 v[18:21], v[198:201], v[186:189], v[134:137]
	v_mfma_f32_16x16x32_bf16 v[46:49], v[174:177], v[190:193], v[30:33]
	v_mfma_f32_16x16x32_bf16 v[26:29], v[170:173], v[146:149], v[26:29]
	v_mfma_f32_16x16x32_bf16 v[30:33], v[214:217], v[190:193], v[18:21]
	v_mfma_f32_16x16x32_bf16 v[18:21], v[198:201], v[146:149], v[138:141]
	v_mfma_f32_16x16x32_bf16 v[42:45], v[174:177], v[194:197], v[26:29]
	v_mfma_f32_16x16x32_bf16 v[22:25], v[178:181], v[186:189], v[22:25]
	v_mfma_f32_16x16x32_bf16 v[26:29], v[214:217], v[194:197], v[18:21]
	v_mfma_f32_16x16x32_bf16 v[18:21], v[238:241], v[186:189], v[142:145]
	v_mfma_f32_16x16x32_bf16 v[38:41], v[182:185], v[190:193], v[22:25]
	v_mfma_f32_16x16x32_bf16 v[22:25], v[242:245], v[190:193], v[18:21]
	v_mfma_f32_16x16x32_bf16 v[18:21], v[238:241], v[146:149], v[150:153]
	v_mfma_f32_16x16x32_bf16 v[18:21], v[242:245], v[194:197], v[18:21]
	s_setprio 0
	s_movk_i32 s0, 0x100
	v_cmp_gt_u32_e32 vcc, s0, v130
	s_barrier
	s_and_saveexec_b64 s[0:1], vcc
	s_mov_b32 s96, s68
	s_mov_b32 s36, s89
	s_cbranch_execz .LBB0_464
	s_barrier
